# v61 + sample-scan item prologue loads batched (16 loads in flight instead of a serialized chain)
# speedup vs baseline: 1.0156x; 1.0088x over previous
.LBB0_833:
	s_or_saveexec_b64 s[0:1], s[0:1]
	v_mov_b32_e32 v48, 7
	s_xor_b64 exec, exec, s[0:1]
	v_mov_b32_e32 v48, 8
	v_lshl_add_u32 v68, s63, 8, v147
	s_or_b64 exec, exec, s[0:1]
	v_ashrrev_i32_e32 v69, 31, v68
	v_readlane_b32 s24, v252, 6
	s_ashr_i32 s0, s62, 3
	v_lshlrev_b64 v[66:67], 2, v[68:69]
	v_readlane_b32 s30, v252, 12
	v_readlane_b32 s31, v252, 13
	s_add_i32 s0, s0, s8
	s_and_b32 s21, s62, -8
	v_lshl_add_u64 v[70:71], s[30:31], 0, v[66:67]
	v_mad_i64_i32 v[70:71], s[6:7], s0, v231, v[70:71]
	v_add_co_u32_e32 v72, vcc, 0x4000, v70
	s_mul_i32 s22, s21, 0x3000
	s_nop 0
	v_addc_co_u32_e32 v73, vcc, 0, v71, vcc
	global_load_dword v138, v[70:71], off
	global_load_dword v139, v[72:73], off
	v_add_co_u32_e32 v70, vcc, 0x8000, v70
	s_add_i32 s1, s21, 0x4000
	s_add_i32 s6, s22, 0xc000000
	v_addc_co_u32_e32 v71, vcc, 0, v71, vcc
	s_mul_hi_i32 s7, s1, 0x3000
	s_add_u32 s6, s4, s6
	global_load_dword v140, v[70:71], off
	s_movk_i32 s23, 0x1000
	v_lshl_add_u32 v71, v68, 1, s23
	v_readlane_b32 s25, v252, 7
	v_readlane_b32 s26, v252, 8
	v_readlane_b32 s27, v252, 9
	v_readlane_b32 s28, v252, 10
	v_readlane_b32 s29, v252, 11
	s_add_i32 s23, s22, 0xc000000
	s_add_u32 s6, s4, s23
	s_addc_u32 s7, s5, 0
	global_load_ushort v141, v71, s[6:7]
	s_add_i32 s23, s22, 0xc003000
	s_add_u32 s6, s4, s23
	s_addc_u32 s7, s5, 0
	global_load_ushort v148, v71, s[6:7]
	s_add_i32 s23, s22, 0xc006000
	s_add_u32 s6, s4, s23
	s_addc_u32 s7, s5, 0
	global_load_ushort v149, v71, s[6:7]
	s_add_i32 s23, s22, 0xc009000
	s_add_u32 s6, s4, s23
	s_addc_u32 s7, s5, 0
	global_load_ushort v69, v71, s[6:7]
	s_add_i32 s23, s22, 0xc00c000
	s_add_u32 s6, s4, s23
	s_addc_u32 s7, s5, 0
	global_load_ushort v68, v71, s[6:7]
	s_add_i32 s23, s22, 0xc00f000
	s_add_u32 s6, s4, s23
	s_addc_u32 s7, s5, 0
	global_load_ushort v150, v71, s[6:7]
	s_add_i32 s23, s22, 0xc012000
	s_add_u32 s6, s4, s23
	s_addc_u32 s7, s5, 0
	global_load_ushort v72, v71, s[6:7]
	s_add_i32 s23, s22, 0xc015000
	s_add_u32 s6, s4, s23
	s_addc_u32 s7, s5, 0
	global_load_ushort v73, v71, s[6:7]
	global_load_dword v151, v66, s[42:43]
	global_load_dword v152, v66, s[82:83]
	global_load_dword v153, v66, s[86:87]
	global_load_dword v70, v66, s[80:81]
	v_readlane_b32 s6, v252, 47
	v_readlane_b32 s7, v252, 48
	s_nop 4
	global_load_dword v66, v66, s[6:7]
	s_waitcnt vmcnt(0)
	v_lshlrev_b32_e32 v141, 16, v141
	v_lshlrev_b32_e32 v148, 16, v148
	v_lshlrev_b32_e32 v149, 16, v149
	v_lshlrev_b32_e32 v69, 16, v69
	v_lshlrev_b32_e32 v68, 16, v68
	v_lshlrev_b32_e32 v150, 16, v150
	v_lshlrev_b32_e32 v72, 16, v72
	v_lshlrev_b32_e32 v73, 16, v73
	v_fma_f32 v67, v138, v151, v66
	v_fmac_f32_e32 v67, v139, v152
	v_fmac_f32_e32 v67, v140, v153
	v_fmac_f32_e32 v67, v70, v141
	v_mul_f32_e32 v71, 0xbfb8aa3b, v67
	v_exp_f32_e32 v71, v71
	s_nop 0
	v_add_f32_e32 v71, 1.0, v71
	v_rcp_f32_e32 v71, v71
	s_nop 0
	v_mul_f32_e32 v67, v67, v71
	ds_write_b32 v219, v67
	v_fma_f32 v67, v139, v151, v66
	v_fmac_f32_e32 v67, v140, v152
	v_fmac_f32_e32 v67, v153, v141
	v_fmac_f32_e32 v67, v70, v148
	v_mul_f32_e32 v71, 0xbfb8aa3b, v67
	v_exp_f32_e32 v71, v71
	s_nop 0
	v_add_f32_e32 v71, 1.0, v71
	v_rcp_f32_e32 v71, v71
	s_nop 0
	v_mul_f32_e32 v67, v67, v71
	v_lshlrev_b32_e64 v71, v48, 1
	v_lshl_add_u32 v71, v71, 2, v219
	ds_write_b32 v71, v67
	v_fma_f32 v67, v140, v151, v66
	v_fmac_f32_e32 v67, v152, v141
	v_fmac_f32_e32 v67, v153, v148
	v_fmac_f32_e32 v67, v70, v149
	v_mul_f32_e32 v71, 0xbfb8aa3b, v67
	v_exp_f32_e32 v71, v71
	s_nop 0
	v_add_f32_e32 v71, 1.0, v71
	v_rcp_f32_e32 v71, v71
	s_nop 0
	v_mul_f32_e32 v67, v67, v71
	v_lshlrev_b32_e64 v71, v48, 2
	v_lshl_add_u32 v71, v71, 2, v219
	ds_write_b32 v71, v67
	v_fma_f32 v67, v151, v141, v66
	v_fmac_f32_e32 v67, v152, v148
	v_fmac_f32_e32 v67, v153, v149
	v_fmac_f32_e32 v67, v70, v69
	v_mul_f32_e32 v71, 0xbfb8aa3b, v67
	v_exp_f32_e32 v71, v71
	s_nop 0
	v_add_f32_e32 v71, 1.0, v71
	v_rcp_f32_e32 v71, v71
	s_nop 0
	v_mul_f32_e32 v67, v67, v71
	v_lshlrev_b32_e64 v71, v48, 3
	v_lshl_add_u32 v71, v71, 2, v219
	ds_write_b32 v71, v67
	v_fma_f32 v67, v151, v148, v66
	v_fmac_f32_e32 v67, v152, v149
	v_fmac_f32_e32 v67, v153, v69
	v_fmac_f32_e32 v67, v70, v68
	v_mul_f32_e32 v71, 0xbfb8aa3b, v67
	v_exp_f32_e32 v71, v71
	s_nop 0
	v_add_f32_e32 v71, 1.0, v71
	v_rcp_f32_e32 v71, v71
	s_nop 0
	v_mul_f32_e32 v67, v67, v71
	v_lshlrev_b32_e64 v71, v48, 4
	v_lshl_add_u32 v71, v71, 2, v219
	ds_write_b32 v71, v67
	v_fma_f32 v67, v151, v149, v66
	v_fmac_f32_e32 v67, v152, v69
	v_fmac_f32_e32 v67, v153, v68
	v_fmac_f32_e32 v67, v70, v150
	v_mul_f32_e32 v71, 0xbfb8aa3b, v67
	v_exp_f32_e32 v71, v71
	s_nop 0
	v_add_f32_e32 v71, 1.0, v71
	v_rcp_f32_e32 v71, v71
	s_nop 0
	v_mul_f32_e32 v67, v67, v71
	v_lshlrev_b32_e64 v71, v48, 5
	v_lshl_add_u32 v71, v71, 2, v219
	ds_write_b32 v71, v67
	v_fma_f32 v67, v151, v69, v66
	v_fmac_f32_e32 v67, v152, v68
	v_fmac_f32_e32 v67, v153, v150
	v_fmac_f32_e32 v67, v70, v72
	v_mul_f32_e32 v69, 0xbfb8aa3b, v67
	v_exp_f32_e32 v69, v69
	v_fmac_f32_e32 v66, v151, v68
	v_fmac_f32_e32 v66, v152, v150
	v_fmac_f32_e32 v66, v153, v72
	v_add_f32_e32 v69, 1.0, v69
	v_rcp_f32_e32 v69, v69
	v_fmac_f32_e32 v66, v70, v73
	v_mul_f32_e32 v67, v67, v69
	v_lshlrev_b32_e64 v69, v48, 6
	v_lshl_add_u32 v69, v69, 2, v219
	ds_write_b32 v69, v67
	v_mul_f32_e32 v67, 0xbfb8aa3b, v66
	v_exp_f32_e32 v67, v67
	v_lshlrev_b32_e64 v48, v48, 7
	v_lshl_add_u32 v48, v48, 2, v219
	v_add_f32_e32 v67, 1.0, v67
	v_rcp_f32_e32 v67, v67
	s_nop 0
	v_mul_f32_e32 v66, v66, v67
	ds_write_b32 v48, v66
	s_mov_b64 s[6:7], exec
	v_readlane_b32 s22, v255, 14
	v_readlane_b32 s23, v255, 15
	s_and_b64 s[22:23], s[6:7], s[22:23]
	s_mov_b64 exec, s[22:23]
	s_cbranch_execz .LBB0_839
	v_add_u32_e32 v66, s1, v213
	v_ashrrev_i32_e32 v67, 31, v66
	v_readlane_b32 s22, v255, 8
	v_lshl_or_b32 v68, s63, 2, v214
	v_lshlrev_b64 v[66:67], 7, v[66:67]
	v_readlane_b32 s23, v255, 9
	v_lshlrev_b32_e32 v48, 2, v68
	v_readlane_b32 s24, v252, 39
	v_lshl_add_u64 v[66:67], s[22:23], 0, v[66:67]
	v_lshl_add_u64 v[66:67], v[66:67], 0, v[48:49]
	v_or_b32_e32 v48, s11, v68
	v_readlane_b32 s28, v252, 43
	v_readlane_b32 s29, v252, 44
	global_load_dword v69, v[66:67], off
	v_readlane_b32 s25, v252, 40
	v_lshl_add_u64 v[66:67], v[48:49], 2, s[28:29]
	global_load_dword v66, v[66:67], off
	v_readlane_b32 s26, v252, 41
	v_readlane_b32 s27, v252, 42
	v_readlane_b32 s30, v252, 45
	v_readlane_b32 s31, v252, 46
	s_waitcnt vmcnt(0)
	v_add_f32_e32 v66, v69, v66
	v_cmp_nlt_f32_e32 vcc, s19, v66
	s_and_saveexec_b64 s[40:41], vcc
	s_cbranch_execz .LBB0_838
	v_mul_f32_e32 v66, 0x3fb8aa3b, v66
	v_exp_f32_e32 v150, v66
	s_mov_b32 s1, 0x3f317218
	v_add_f32_e32 v68, 1.0, v150
	v_frexp_mant_f32_e32 v70, v68
	v_cvt_f64_f32_e32 v[66:67], v68
	v_frexp_exp_i32_f64_e32 v66, v[66:67]
	v_cmp_gt_f32_e32 vcc, s64, v70
	v_add_f32_e32 v69, -1.0, v68
	v_sub_f32_e32 v71, v69, v68
	v_subbrev_co_u32_e32 v138, vcc, 0, v66, vcc
	v_sub_u32_e32 v66, 0, v138
	v_sub_f32_e32 v69, v150, v69
	v_add_f32_e32 v71, 1.0, v71
	v_ldexp_f32 v67, v68, v66
	v_add_f32_e32 v69, v69, v71
	v_add_f32_e32 v68, -1.0, v67
	v_add_f32_e32 v70, 1.0, v67
	v_ldexp_f32 v66, v69, v66
	v_add_f32_e32 v69, 1.0, v68
	v_add_f32_e32 v71, -1.0, v70
	v_sub_f32_e32 v69, v67, v69
	v_sub_f32_e32 v67, v67, v71
	v_add_f32_e32 v69, v66, v69
	v_add_f32_e32 v66, v66, v67
	v_add_f32_e32 v139, v70, v66
	v_rcp_f32_e32 v141, v139
	v_sub_f32_e32 v67, v139, v70
	v_sub_f32_e32 v140, v66, v67
	v_add_f32_e32 v67, v68, v69
	v_mul_f32_e32 v149, v67, v141
	v_sub_f32_e32 v66, v67, v68
	v_mul_f32_e32 v68, v139, v149
	v_fma_f32 v70, v149, v139, -v68
	v_fmac_f32_e32 v70, v149, v140
	v_sub_f32_e32 v148, v69, v66
	v_add_f32_e32 v66, v68, v70
	v_sub_f32_e32 v69, v67, v66
	v_pk_add_f32 v[72:73], v[66:67], v[68:69] neg_lo:[0,1] neg_hi:[0,1]
	v_mov_b32_e32 v71, v66
	v_pk_add_f32 v[66:67], v[72:73], v[70:71] neg_lo:[0,1] neg_hi:[0,1]
	s_nop 0
	v_add_f32_e32 v67, v148, v67
	v_add_f32_e32 v66, v66, v67
	v_add_f32_e32 v67, v69, v66
	v_mul_f32_e32 v148, v141, v67
	v_mul_f32_e32 v68, v139, v148
	v_fma_f32 v70, v148, v139, -v68
	v_fmac_f32_e32 v70, v148, v140
	v_sub_f32_e32 v69, v69, v67
	v_add_f32_e32 v139, v66, v69
	v_add_f32_e32 v66, v68, v70
	v_sub_f32_e32 v69, v67, v66
	v_pk_add_f32 v[72:73], v[66:67], v[68:69] neg_lo:[0,1] neg_hi:[0,1]
	v_mov_b32_e32 v71, v66
	v_pk_add_f32 v[66:67], v[72:73], v[70:71] neg_lo:[0,1] neg_hi:[0,1]
	s_nop 0
	v_add_f32_e32 v67, v139, v67
	v_add_f32_e32 v66, v66, v67
	v_add_f32_e32 v67, v149, v148
	v_add_f32_e32 v66, v69, v66
	v_sub_f32_e32 v68, v67, v149
	v_mul_f32_e32 v66, v141, v66
	v_sub_f32_e32 v68, v148, v68
	v_add_f32_e32 v68, v68, v66
	v_add_f32_e32 v70, v67, v68
	v_mul_f32_e32 v71, v70, v70
	v_fmamk_f32 v66, v71, 0x3e9b6dac, v236
	v_fmaak_f32 v207, v71, v66, 0x3f2aaada
	v_cvt_f32_i32_e32 v66, v138
	v_sub_f32_e32 v67, v70, v67
	v_sub_f32_e32 v67, v68, v67
	v_ldexp_f32 v72, v67, 1
	v_mul_f32_e32 v67, v70, v71
	v_ldexp_f32 v69, v70, 1
	v_pk_mul_f32 v[70:71], v[66:67], v[206:207]
	s_nop 0
	v_fma_f32 v68, v66, s1, -v70
	v_fmac_f32_e32 v68, 0xb102e308, v66
	v_pk_add_f32 v[66:67], v[70:71], v[68:69]
	s_mov_b32 s1, 0x7f800000
	v_sub_f32_e32 v69, v67, v69
	v_sub_f32_e32 v69, v71, v69
	v_add_f32_e32 v73, v72, v69
	v_mov_b32_e32 v72, v70
	v_pk_add_f32 v[70:71], v[66:67], v[70:71] neg_lo:[0,1] neg_hi:[0,1]
	v_pk_add_f32 v[138:139], v[66:67], v[72:73]
	v_mov_b32_e32 v69, v66
	v_mov_b32_e32 v71, v139
	v_pk_add_f32 v[140:141], v[68:69], v[70:71] neg_lo:[0,1] neg_hi:[0,1]
	v_pk_add_f32 v[68:69], v[68:69], v[70:71]
	v_mov_b32_e32 v72, v73
	v_pk_add_f32 v[70:71], v[68:69], v[66:67] op_sel:[1,0] op_sel_hi:[0,1] neg_lo:[0,1] neg_hi:[0,1]
	v_pk_add_f32 v[148:149], v[138:139], v[70:71] op_sel_hi:[1,0] neg_lo:[0,1] neg_hi:[0,1]
	v_mov_b32_e32 v138, v139
	v_mov_b32_e32 v139, v69
	v_pk_mov_b32 v[70:71], v[66:67], v[70:71] op_sel:[1,0]
	v_mov_b32_e32 v73, v66
	v_pk_add_f32 v[70:71], v[138:139], v[70:71] neg_lo:[0,1] neg_hi:[0,1]
	v_mov_b32_e32 v148, v140
	v_pk_add_f32 v[66:67], v[72:73], v[70:71] neg_lo:[0,1] neg_hi:[0,1]
	v_mov_b32_e32 v141, v69
	v_pk_add_f32 v[70:71], v[148:149], v[66:67]
	v_cmp_neq_f32_e32 vcc, s1, v150
	v_pk_add_f32 v[72:73], v[70:71], v[70:71] op_sel:[0,1] op_sel_hi:[1,0]
	s_mov_b32 s1, 0x33800000
	v_pk_add_f32 v[68:69], v[68:69], v[72:73] op_sel:[1,0] op_sel_hi:[0,1]
	v_mov_b32_e32 v71, v68
	v_pk_add_f32 v[138:139], v[70:71], v[140:141] neg_lo:[0,1] neg_hi:[0,1]
	v_mov_b32_e32 v67, v72
	v_sub_f32_e32 v69, v70, v138
	v_pk_add_f32 v[66:67], v[66:67], v[138:139] neg_lo:[0,1] neg_hi:[0,1]
	v_sub_f32_e32 v69, v140, v69
	v_add_f32_e32 v66, v66, v69
	v_add_f32_e32 v66, v66, v67
	v_add_f32_e32 v66, v68, v66
	v_cndmask_b32_e32 v66, v237, v66, vcc
	v_cmp_ngt_f32_e32 vcc, -1.0, v150
	s_nop 1
	v_cndmask_b32_e32 v66, v238, v66, vcc
	v_cmp_neq_f32_e32 vcc, -1.0, v150
	s_nop 1
	v_cndmask_b32_e32 v66, v239, v66, vcc
	v_cmp_lt_f32_e64 vcc, |v150|, s1
	s_nop 1
	v_cndmask_b32_e32 v66, v66, v150, vcc
